# GQA item prologue: second key/value tile loads issued with the first batch (addresses = first tile + 64 rows) instead of after the first QK^T
# speedup vs baseline: 1.0063x; 1.0063x over previous
; __device__ __forceinline__ int v_st(int k, int c) { const int kk = (k & ~0xC) | ((k & 4) << 1) | ((k & 8) >> 1); return ((kk >> 3) * 4 + (c >> 5)) * 512 + ((kk & 7) * 32 + (c & 31)) * 2; }
; __device__ __forceinline__ int v_rd_base(int lane) { return ((lane & 3) << 3) | (((lane >> 2) & 3) << 6) | (((lane >> 4) & 1) << 5) | (((lane >> 5) & 1) << 8); }
; #define SLOAD(i, k0) do { sr_[i].vs0 = *reinterpret_cast<const bf16x8*>(&Vh[(long)((k0) + sr) * LDP + sc]); sr_[i].vs1 = *reinterpret_cast<const bf16x8*>(&Vh[(long)((k0) + 32 + sr) * LDP + sc]); \
;     sr_[i].ks0 = *reinterpret_cast<const bf16x8*>(&Kh[(long)((k0) + ksr) * LDP + ksc]); if (DK == 128) sr_[i].ks1 = *reinterpret_cast<const bf16x8*>(&Kh[(long)((k0) + 32 + ksr) * LDP + ksc]); } while (0)
; #define SWAIT() do { if (SD == 1) asm volatile("s_waitcnt vmcnt(0)" ::: "memory"); else if (DK == 128) asm volatile("s_waitcnt vmcnt(4)" ::: "memory"); else asm volatile("s_waitcnt vmcnt(3)" ::: "memory"); } while (0)
; #define HOOK(P0, P1, j) do { if (NA) na_hook(P0, P1, krow0 + (j), q_row, q_col, win_r, win_c, rpb, inv_scale, hi); } while (0)
; template <int DK, bool NA, bool QL, int SD> ...
;     ...
;   const bf16* Qw = Qb + (long)(wid * 32 + r32) * LDP + hi * 8;
; #pragma unroll
;   for (int d0 = 0; d0 < DK / 16; ++d0) { const bf16x8 qv = *reinterpret_cast<const bf16x8*>(Qw + d0 * 16); if (QL) *reinterpret_cast<bf16x8*>(ql + d0 * 1024) = qv; else qr[d0] = qv; }
;   const int sr = tid >> 4, sc = (tid & 15) * 8, vst0 = v_st(sr, sc), vst1 = v_st(32 + sr, sc);
;   const int ksr = DK == 128 ? sr : (tid >> 3), ksc = DK == 128 ? sc : (tid & 7) * 8;
;   const int vb0 = (int)(uintptr_t)V_lds + v_rd_base(lane);
;   struct { bf16x8 vs0, vs1, ks0, ks1; } sr_[SD];
;     ...
;   f32x16 pA0, pA1, pB0, pB1; float mnA, mnB, alA, alB; bf16x8 pa0, pa1, pa2, pa3;
;   constexpr int SE = 0, SO = SD - 1;
;   SLOAD(SE, 0); asm volatile("s_waitcnt vmcnt(0)" ::: "memory"); SWRITE(0, SE); __syncthreads();
;   qkt<DK, QL>(pA0, pA1, K_lds, qr, ql, r32, hi); HOOK(pA0, pA1, 0); partialSM(pA0, pA1, m_reg, mnA, alA, C, thrRaw);
;   SLOAD(SO, KVBLK); if (SD == 2) { if (2 < NT) SLOAD(SE, 2 * KVBLK); }
;   SWAIT(); SWRITE(1, SO); __syncthreads();
.LBB0_658:
	s_and_b64 vcc, exec, s[0:1]
	s_cbranch_vccz .LBB0_679
	v_mov_b32_e32 v50, v188
	v_readlane_b32 s0, v253, 11
	v_readlane_b32 s1, v253, 12
	v_ashrrev_i32_e32 v53, 6, v50
	v_and_b32_e32 v51, 31, v50
	v_lshl_or_b32 v0, v53, 5, v51
	v_mov_b64_e32 v[2:3], s[0:1]
	s_movk_i32 s3, 0x2800
	v_mad_i64_i32 v[2:3], s[0:1], v0, s3, v[2:3]
	v_lshrrev_b32_e32 v0, 1, v50
	v_and_b32_e32 v0, 16, v0
	v_ashrrev_i32_e32 v52, 4, v50
	v_bfe_u32 v178, v52, 2, 1
	v_bfe_u32 v179, v52, 3, 1
	v_sub_u32_e32 v178, v178, v179
	v_mul_i32_i24_e32 v178, 0xa000, v178
	v_ashrrev_i32_e32 v179, 31, v178
	v_lshl_add_u64 v[30:31], v[2:3], 0, v[0:1]
	v_lshlrev_b32_e32 v54, 3, v50
	v_add_u32_e32 v55, 32, v52
	s_movk_i32 s9, 0x1400
	global_load_dwordx4 v[2:5], v[30:31], off
	global_load_dwordx4 v[6:9], v[30:31], off offset:32
	global_load_dwordx4 v[10:13], v[30:31], off offset:64
	global_load_dwordx4 v[14:17], v[30:31], off offset:96
	global_load_dwordx4 v[18:21], v[30:31], off offset:128
	global_load_dwordx4 v[22:25], v[30:31], off offset:160
	global_load_dwordx4 v[26:29], v[30:31], off offset:192
	s_nop 0
	global_load_dwordx4 v[30:33], v[30:31], off offset:224
	v_and_b32_e32 v71, 0x78, v54
	v_mad_i64_i32 v[34:35], s[0:1], v52, s9, 0
	v_mad_i64_i32 v[36:37], s[0:1], v55, s9, 0
	v_or_b32_e32 v34, v34, v71
	v_readlane_b32 s6, v253, 15
	v_or_b32_e32 v36, v36, v71
	v_readlane_b32 s4, v253, 13
	v_lshlrev_b64 v[42:43], 1, v[34:35]
	v_readlane_b32 s7, v253, 16
	v_lshlrev_b64 v[44:45], 1, v[36:37]
	v_readlane_b32 s5, v253, 14
	v_lshl_add_u64 v[34:35], s[6:7], 0, v[42:43]
	v_lshl_add_u64 v[34:35], v[34:35], 0, v[178:179]
	v_lshl_add_u64 v[38:39], s[6:7], 0, v[44:45]
	v_lshl_add_u64 v[38:39], v[38:39], 0, v[178:179]
	v_lshl_add_u64 v[42:43], s[4:5], 0, v[42:43]
	v_lshl_add_u64 v[46:47], s[4:5], 0, v[44:45]
	v_mov_b32_e32 v236, 0xa0000
	v_mov_b32_e32 v237, 0
	v_lshl_add_u64 v[220:221], v[34:35], 0, v[236:237]
	v_lshl_add_u64 v[224:225], v[38:39], 0, v[236:237]
	v_lshl_add_u64 v[228:229], v[42:43], 0, v[236:237]
	v_lshl_add_u64 v[232:233], v[46:47], 0, v[236:237]
	global_load_dwordx4 v[34:37], v[34:35], off
	s_nop 0
	global_load_dwordx4 v[38:41], v[38:39], off
	s_nop 0
	global_load_dwordx4 v[42:45], v[42:43], off
	s_nop 0
	global_load_dwordx4 v[46:49], v[46:47], off
	global_load_dwordx4 v[220:223], v[220:221], off
	global_load_dwordx4 v[224:227], v[224:225], off
	global_load_dwordx4 v[228:231], v[228:229], off
	global_load_dwordx4 v[232:235], v[232:233], off
	v_and_b32_e32 v72, 63, v50
	v_readlane_b32 s0, v254, 57
	v_lshlrev_b32_e32 v57, 4, v72
	v_and_b32_e32 v58, 0xfffff0, v52
	v_lshl_add_u32 v53, v53, 13, s0
	v_lshlrev_b32_e32 v59, 1, v52
	v_lshrrev_b32_e32 v60, 1, v52
	v_and_b32_e32 v61, 3, v52
	v_add_u32_e32 v153, v53, v57
	v_and_or_b32 v53, v59, 8, v58
	v_and_or_b32 v58, v60, 4, v61
	v_and_b32_e32 v60, 0xfffff0, v55
	v_lshlrev_b32_e32 v61, 1, v55
	v_and_b32_e32 v56, 0xf0, v50
	v_bfe_u32 v54, v54, 5, 2
	v_lshlrev_b32_e32 v62, 8, v52
	v_lshlrev_b32_e32 v59, 1, v71
	v_lshlrev_b32_e32 v55, 8, v55
	v_lshrrev_b32_e32 v53, 1, v53
	v_and_or_b32 v60, v61, 8, v60
	v_bitop3_b32 v61, v59, v62, v56 bitop3:0xde
	v_bitop3_b32 v55, v59, v55, v56 bitop3:0xde
	v_or_b32_e32 v53, v53, v54
	v_lshrrev_b32_e32 v56, 1, v60
	v_lshlrev_b32_e32 v58, 6, v58
	v_and_b32_e32 v63, 48, v59
	v_lshlrev_b32_e32 v53, 9, v53
	v_or_b32_e32 v54, v56, v54
	v_or3_b32 v53, v53, v58, v63
	v_lshlrev_b32_e32 v54, 9, v54
	v_or3_b32 v54, v54, v58, v63
	v_add_u32_e32 v209, 0, v53
	v_lshlrev_b32_e32 v53, 8, v51
	v_add_u32_e32 v177, 0, v61
	v_add_u32_e32 v208, 0, v55
	v_add_u32_e32 v210, 0, v54
	v_and_b32_e32 v54, 0x3fffffc0, v50
	s_add_i32 s0, 0, 0x10000
	v_lshl_add_u32 v148, v54, 2, s0
	v_readlane_b32 s12, v254, 62
	s_cmp_lg_u32 0, -1
	v_readlane_b32 s13, v254, 63
	v_readlane_b32 s14, v255, 0
	v_readlane_b32 s15, v255, 1
	s_mov_b32 s8, -1
	s_cselect_b32 s2, 0, 0
	v_readlane_b32 s16, v255, 2
	v_readlane_b32 s17, v255, 3
	s_waitcnt vmcnt(15)
	ds_write_b128 v153, v[2:5]
	s_waitcnt vmcnt(14)
	ds_write_b128 v153, v[6:9] offset:1024
	s_waitcnt vmcnt(13)
	ds_write_b128 v153, v[10:13] offset:2048
	s_waitcnt vmcnt(12)
	ds_write_b128 v153, v[14:17] offset:3072
	s_waitcnt vmcnt(11)
	ds_write_b128 v153, v[18:21] offset:4096
	s_waitcnt vmcnt(10)
	ds_write_b128 v153, v[22:25] offset:5120
	s_waitcnt vmcnt(9)
	ds_write_b128 v153, v[26:29] offset:6144
	s_waitcnt vmcnt(8)
	ds_write_b128 v153, v[30:33] offset:7168
	v_lshlrev_b32_e32 v2, 4, v50
	v_and_b32_e32 v58, 0xf0, v2
	v_bitop3_b32 v2, v0, v53, v58 bitop3:0xde
	v_add_u32_e32 v159, 0, v2
	s_waitcnt vmcnt(0)
	s_waitcnt vmcnt(3)
	ds_write_b128 v209, v[34:37]
	s_waitcnt vmcnt(2)
	ds_write_b128 v210, v[38:41]
	s_waitcnt vmcnt(1)
	ds_write_b128 v177, v[42:45] offset:32768
	s_waitcnt vmcnt(0)
	ds_write_b128 v208, v[46:49] offset:32768
	s_waitcnt lgkmcnt(0)
	s_barrier
; #define HOOK(P0, P1, j) do { if (NA) na_hook(P0, P1, krow0 + (j), q_row, q_col, win_r, win_c, rpb, inv_scale, hi); } while (0)
; template <int DK, bool QL>
; __device__ __forceinline__ void qkt(f32x16& p0, f32x16& p1, const bf16* Ks, const bf16x8* qr, const char* ql, int r32, int hi) {
;   p0 = f32x16{}; p1 = f32x16{};
; #pragma unroll
;   for (int d0 = 0; d0 < DK / 16; ++d0) { int cb = (d0 * 16 + hi * 8) * 2;
;     const bf16x8 qv = QL ? *reinterpret_cast<const bf16x8*>(ql + d0 * 1024) : qr[d0];
;     bf16x8 b0 = *reinterpret_cast<const bf16x8*>((const char*)Ks + kswz<DK>(r32, cb));
;     bf16x8 b1 = *reinterpret_cast<const bf16x8*>((const char*)Ks + kswz<DK>(32 + r32, cb));
;     p0 = __builtin_amdgcn_mfma_f32_32x32x16_bf16(b0, qv, p0, 0, 0, 0);
;     p1 = __builtin_amdgcn_mfma_f32_32x32x16_bf16(b1, qv, p1, 0, 0, 0); }
; }
; template <int DK, bool NA, bool QL, int SD> ...
;     ...
;   qkt<DK, QL>(pA0, pA1, K_lds, qr, ql, r32, hi); HOOK(pA0, pA1, 0); partialSM(pA0, pA1, m_reg, mnA, alA, C, thrRaw);
	ds_read_b128 v[2:5], v159 offset:32768
	ds_read_b128 v[6:9], v153
	ds_read_b128 v[10:13], v159 offset:40960
	ds_read_b128 v[14:17], v153 offset:1024
	s_waitcnt lgkmcnt(2)
	v_mfma_f32_32x32x16_bf16 v[34:49], v[2:5], v[6:9], 0
	v_or_b32_e32 v2, 32, v0
	v_bitop3_b32 v2, v2, v53, v58 bitop3:0xde
	v_add_u32_e32 v207, 0, v2
	v_readlane_b32 s18, v255, 4
	v_readlane_b32 s19, v255, 5
	v_readlane_b32 s20, v255, 6
	v_readlane_b32 s21, v255, 7
	s_waitcnt lgkmcnt(1)
	v_mfma_f32_32x32x16_bf16 v[18:33], v[10:13], v[6:9], 0
	ds_read_b128 v[2:5], v207 offset:32768
	ds_read_b128 v[6:9], v207 offset:40960
	v_readlane_b32 s22, v255, 8
	v_readlane_b32 s23, v255, 9
	v_readlane_b32 s24, v255, 10
	v_readlane_b32 s25, v255, 11
	v_readlane_b32 s26, v255, 12
	v_readlane_b32 s27, v255, 13
	s_waitcnt lgkmcnt(1)
	v_mfma_f32_32x32x16_bf16 v[34:49], v[2:5], v[14:17], v[34:49]
	v_or_b32_e32 v2, 64, v0
	v_bitop3_b32 v2, v2, v53, v58 bitop3:0xde
	v_add_u32_e32 v161, 0, v2
	s_mov_b32 s12, s13
	s_mov_b32 s14, s13
	s_mov_b32 s15, s13
	s_mov_b32 s1, s13
	s_waitcnt lgkmcnt(0)
	v_mfma_f32_32x32x16_bf16 v[18:33], v[6:9], v[14:17], v[18:33]
	ds_read_b128 v[2:5], v161 offset:32768
	ds_read_b128 v[6:9], v153 offset:2048
	ds_read_b128 v[10:13], v161 offset:40960
	ds_read_b128 v[14:17], v153 offset:3072
	s_mov_b32 s16, s13
	s_mov_b32 s17, s13
	s_mov_b32 s18, s13
	s_mov_b32 s19, s13
	s_mov_b32 s20, s13
	s_mov_b32 s21, s13
	s_waitcnt lgkmcnt(2)
	v_mfma_f32_32x32x16_bf16 v[34:49], v[2:5], v[6:9], v[34:49]
	v_or_b32_e32 v2, 0x60, v0
	v_bitop3_b32 v2, v2, v53, v58 bitop3:0xde
	v_add_u32_e32 v160, 0, v2
	s_mov_b32 s22, s13
	s_mov_b32 s23, s13
	s_mov_b32 s24, s13
	s_mov_b32 s25, s13
	s_waitcnt lgkmcnt(1)
	v_mfma_f32_32x32x16_bf16 v[18:33], v[10:13], v[6:9], v[18:33]
	ds_read_b128 v[2:5], v160 offset:32768
	ds_read_b128 v[6:9], v160 offset:40960
	s_mov_b32 s26, s13
	s_mov_b32 s27, s13
	v_mov_b32_e32 v150, 0
	v_lshl_add_u32 v149, v51, 2, v148
	v_mov_b32_e32 v51, v150
	s_waitcnt lgkmcnt(1)
	v_mfma_f32_32x32x16_bf16 v[34:49], v[2:5], v[14:17], v[34:49]
	v_or_b32_e32 v2, 0x80, v0
	v_bitop3_b32 v2, v2, v53, v58 bitop3:0xde
	v_add_u32_e32 v158, 0, v2
	s_waitcnt lgkmcnt(0)
	v_mfma_f32_32x32x16_bf16 v[18:33], v[6:9], v[14:17], v[18:33]
	ds_read_b128 v[2:5], v158 offset:32768
	ds_read_b128 v[6:9], v153 offset:4096
	ds_read_b128 v[10:13], v158 offset:40960
	ds_read_b128 v[14:17], v153 offset:5120
	s_waitcnt lgkmcnt(2)
	v_mfma_f32_32x32x16_bf16 v[34:49], v[2:5], v[6:9], v[34:49]
	v_or_b32_e32 v2, 0xa0, v0
	v_bitop3_b32 v2, v2, v53, v58 bitop3:0xde
	v_add_u32_e32 v156, 0, v2
	ds_read_b128 v[2:5], v156 offset:32768
	s_waitcnt lgkmcnt(2)
	v_mfma_f32_32x32x16_bf16 v[18:33], v[10:13], v[6:9], v[18:33]
	v_lshlrev_b32_e32 v10, 3, v72
	v_and_b32_e32 v6, 0xc0, v57
	v_and_or_b32 v11, v10, 24, v6
	ds_read_b128 v[6:9], v156 offset:40960
	v_lshlrev_b32_e32 v12, 1, v50
	s_waitcnt lgkmcnt(0)
	v_mfma_f32_32x32x16_bf16 v[18:33], v[6:9], v[14:17], v[18:33]
	ds_read_b128 v[6:9], v153 offset:6144
	v_mfma_f32_32x32x16_bf16 v[34:49], v[2:5], v[14:17], v[34:49]
	v_and_b32_e32 v2, 32, v12
	v_and_b32_e32 v3, 0x100, v10
	v_or3_b32 v73, v11, v2, v3
	v_or_b32_e32 v2, 0xc0, v0
	v_bitop3_b32 v2, v2, v53, v58 bitop3:0xde
	v_add_u32_e32 v157, 0, v2
	ds_read_b128 v[2:5], v157 offset:32768
	s_waitcnt lgkmcnt(0)
	v_mfma_f32_32x32x16_bf16 v[34:49], v[2:5], v[6:9], v[34:49]
	v_or_b32_e32 v2, 0xe0, v0
	v_bitop3_b32 v2, v2, v53, v58 bitop3:0xde
	v_add_u32_e32 v176, 0, v2
	ds_read_b128 v[10:13], v157 offset:40960
	ds_read_b128 v[54:57], v153 offset:7168
	ds_read_b128 v[2:5], v176 offset:32768
	ds_read_b128 v[58:61], v176 offset:40960
	v_add_u32_e32 v152, s2, v73
	s_waitcnt lgkmcnt(3)
	v_mfma_f32_32x32x16_bf16 v[18:33], v[10:13], v[6:9], v[18:33]
	v_writelane_b32 v254, s0, 62
	s_nop 1
	v_writelane_b32 v255, s2, 0
	v_writelane_b32 v255, s3, 1
	v_writelane_b32 v255, s4, 2
	v_writelane_b32 v255, s5, 3
	s_waitcnt lgkmcnt(1)
	v_mfma_f32_32x32x16_bf16 v[34:49], v[2:5], v[54:57], v[34:49]
	v_writelane_b32 v255, s6, 4
	v_writelane_b32 v255, s7, 5
	v_writelane_b32 v255, s8, 6
	v_writelane_b32 v255, s9, 7
	v_writelane_b32 v255, s10, 8
	v_writelane_b32 v255, s11, 9
	v_writelane_b32 v255, s12, 10
	s_waitcnt lgkmcnt(0)
; #define SLOAD(i, k0) do { sr_[i].vs0 = *reinterpret_cast<const bf16x8*>(&Vh[(long)((k0) + sr) * LDP + sc]); sr_[i].vs1 = *reinterpret_cast<const bf16x8*>(&Vh[(long)((k0) + 32 + sr) * LDP + sc]); \
;     sr_[i].ks0 = *reinterpret_cast<const bf16x8*>(&Kh[(long)((k0) + ksr) * LDP + ksc]); if (DK == 128) sr_[i].ks1 = *reinterpret_cast<const bf16x8*>(&Kh[(long)((k0) + 32 + ksr) * LDP + ksc]); } while (0)
; #define SWAIT() do { if (SD == 1) asm volatile("s_waitcnt vmcnt(0)" ::: "memory"); else if (DK == 128) asm volatile("s_waitcnt vmcnt(4)" ::: "memory"); else asm volatile("s_waitcnt vmcnt(3)" ::: "memory"); } while (0)
; #define HOOK(P0, P1, j) do { if (NA) na_hook(P0, P1, krow0 + (j), q_row, q_col, win_r, win_c, rpb, inv_scale, hi); } while (0)
; __device__ __forceinline__ void partialSM(f32x16& p0, f32x16& p1, float& m_reg, float& mn, float& alpha, float C, float thrRaw) {
;   float pmax = p0[0];
; #pragma unroll
;   for (int r = 1; r < 16; ++r) pmax = fmaxf(pmax, p0[r]);
; #pragma unroll
;   for (int r = 0; r < 16; ++r) pmax = fmaxf(pmax, p1[r]);
;   { auto rr = __builtin_amdgcn_permlane32_swap(__float_as_uint(pmax), __float_as_uint(pmax), false, false);
;     pmax = fmaxf(__uint_as_float(rr[0]), __uint_as_float(rr[1])); }
;   if (__builtin_expect(__all(pmax - m_reg <= thrRaw), 1)) { mn = m_reg; alpha = 1.f; }
;   else { mn = fmaxf(m_reg, pmax); alpha = __builtin_amdgcn_exp2f((m_reg - mn) * C); m_reg = mn; }
;   float mnC = -mn * C;
; #pragma unroll
;   for (int r = 0; r < 16; ++r) p0[r] = fmaf(p0[r], C, mnC);
; #pragma unroll
;   for (int r = 0; r < 16; ++r) p1[r] = fmaf(p1[r], C, mnC);
; #pragma unroll
;   for (int r = 0; r < 16; ++r) p0[r] = __builtin_amdgcn_exp2f(p0[r]);
; template <int DK, bool NA, bool QL, int SD> ...
;     ...
;   SLOAD(SE, 0); asm volatile("s_waitcnt vmcnt(0)" ::: "memory"); SWRITE(0, SE); __syncthreads();
;   qkt<DK, QL>(pA0, pA1, K_lds, qr, ql, r32, hi); HOOK(pA0, pA1, 0); partialSM(pA0, pA1, m_reg, mnA, alA, C, thrRaw);
;   SLOAD(SO, KVBLK); if (SD == 2) { if (2 < NT) SLOAD(SE, 2 * KVBLK); }
;   SWAIT(); SWRITE(1, SO); __syncthreads();
	v_mfma_f32_32x32x16_bf16 v[18:33], v[58:61], v[54:57], v[18:33]
	s_nop 2
	v_max_f32_e32 v53, v35, v35
	v_max_f32_e32 v54, v34, v34
	v_max_f32_e32 v53, v54, v53
	v_max3_f32 v53, v53, v36, v37
	v_max3_f32 v53, v53, v38, v39
	v_max3_f32 v53, v53, v40, v41
	v_max3_f32 v53, v53, v42, v43
	v_max3_f32 v53, v53, v44, v45
	v_max3_f32 v53, v53, v46, v47
	v_max3_f32 v53, v53, v48, v49
	v_max3_f32 v53, v53, v18, v19
	v_max3_f32 v53, v53, v20, v21
	v_max3_f32 v53, v53, v22, v23
	v_max3_f32 v53, v53, v24, v25
	v_max3_f32 v53, v53, v26, v27
	v_max3_f32 v53, v53, v28, v29
	v_max3_f32 v53, v53, v30, v31
	v_max3_f32 v53, v53, v32, v33
	v_mov_b32_e32 v70, v53
	v_writelane_b32 v255, s13, 11
	s_nop 0
	v_permlane32_swap_b32_e32 v53, v70
	v_writelane_b32 v255, s14, 12
	v_add_u32_e32 v54, 64, v52
	v_add_u32_e32 v56, 0x60, v52
	v_max_f32_e32 v70, v70, v70
	v_max_f32_e32 v53, v53, v53
	v_writelane_b32 v254, s1, 63
	v_writelane_b32 v255, s15, 13
	v_mad_i64_i32 v[54:55], s[0:1], v54, s9, 0
	v_mad_i64_i32 v[56:57], s[0:1], v56, s9, 0
	v_max_f32_e32 v53, v53, v70
	v_add_f32_e32 v70, 0x7149f2ca, v53
	s_mov_b32 s0, 0x42b504f3
	v_max_f32_e32 v53, 0xf149f2ca, v53
	v_cmp_ge_f32_e32 vcc, s0, v70
	v_sub_f32_e32 v70, 0xf149f2ca, v53
	v_mul_f32_e32 v70, 0x3e0293ee, v70
	v_exp_f32_e32 v70, v70
	s_cmp_eq_u64 vcc, exec
	s_cselect_b64 vcc, -1, 0
	v_cndmask_b32_e32 v134, v53, v199, vcc
	v_cndmask_b32_e64 v211, v70, 1.0, vcc
	v_mul_f32_e32 v70, 0xbe0293ee, v134
	v_fmamk_f32 v53, v34, 0x3e0293ee, v70
	v_add_u32_e32 v34, 0xa0, v52
	v_or_b32_e32 v54, v54, v71
	v_or_b32_e32 v56, v56, v71
	v_fmamk_f32 v74, v35, 0x3e0293ee, v70
	v_fmamk_f32 v77, v38, 0x3e0293ee, v70
	v_mad_i64_i32 v[34:35], s[0:1], v34, s9, 0
	v_add_u32_e32 v38, 0x80, v52
	v_lshlrev_b64 v[62:63], 1, v[54:55]
	v_lshlrev_b64 v[64:65], 1, v[56:57]
	v_fmamk_f32 v78, v39, 0x3e0293ee, v70
	v_or_b32_e32 v34, v34, v71
	v_mad_i64_i32 v[38:39], s[0:1], v38, s9, 0
	v_lshl_add_u64 v[54:55], s[6:7], 0, v[62:63]
	v_lshl_add_u64 v[54:55], v[54:55], 0, v[178:179]
	v_lshl_add_u64 v[58:59], s[6:7], 0, v[64:65]
	v_lshl_add_u64 v[58:59], v[58:59], 0, v[178:179]
	v_lshl_add_u64 v[62:63], s[4:5], 0, v[62:63]
	v_lshl_add_u64 v[66:67], s[4:5], 0, v[64:65]
	v_lshlrev_b64 v[34:35], 1, v[34:35]
	v_or_b32_e32 v38, v38, v71
	s_nop 0
	s_nop 0
	s_nop 0
	v_fmamk_f32 v75, v36, 0x3e0293ee, v70
	v_fmamk_f32 v76, v37, 0x3e0293ee, v70
	v_lshl_add_u64 v[36:37], s[4:5], 0, v[34:35]
	v_lshlrev_b64 v[38:39], 1, v[38:39]
	v_lshl_add_u64 v[34:35], s[6:7], 0, v[34:35]
	v_lshl_add_u64 v[34:35], v[34:35], 0, v[178:179]
	v_fmamk_f32 v79, v40, 0x3e0293ee, v70
	v_fmamk_f32 v80, v41, 0x3e0293ee, v70
	v_lshl_add_u64 v[40:41], s[4:5], 0, v[38:39]
	global_load_dwordx4 v[102:105], v[36:37], off
	global_load_dwordx4 v[98:101], v[40:41], off
	v_lshl_add_u64 v[36:37], s[6:7], 0, v[38:39]
	v_lshl_add_u64 v[36:37], v[36:37], 0, v[178:179]
	global_load_dwordx4 v[110:113], v[34:35], off
	global_load_dwordx4 v[106:109], v[36:37], off
	v_mov_b32_e32 v36, v70
	s_mov_b32 s0, 0x3e0293ee
	s_addk_i32 s2, 0x4000
	v_fmamk_f32 v42, v42, 0x3e0293ee, v70
	v_fmamk_f32 v43, v43, 0x3e0293ee, v70
	v_fmamk_f32 v44, v44, 0x3e0293ee, v70
	v_fmamk_f32 v45, v45, 0x3e0293ee, v70
	v_fmamk_f32 v46, v46, 0x3e0293ee, v70
	v_fmamk_f32 v34, v47, 0x3e0293ee, v70
	v_fmamk_f32 v35, v48, 0x3e0293ee, v70
	v_fmac_f32_e32 v36, 0x3e0293ee, v49
	v_pk_fma_f32 v[126:127], v[18:19], s[0:1], v[70:71] op_sel_hi:[1,0,0]
	v_add_u32_e32 v151, s2, v73
	v_mad_i64_i32 v[18:19], s[2:3], v52, s3, 0
	v_mov_b64_e32 v[2:3], s[12:13]
	v_pk_fma_f32 v[124:125], v[20:21], s[0:1], v[70:71] op_sel_hi:[1,0,0]
	v_exp_f32_e32 v145, v53
	v_exp_f32_e32 v216, v74
	v_exp_f32_e32 v131, v75
	v_exp_f32_e32 v215, v76
	v_exp_f32_e32 v132, v77
	v_exp_f32_e32 v144, v78
	v_exp_f32_e32 v133, v79
	v_exp_f32_e32 v143, v80
	v_exp_f32_e32 v140, v42
	v_exp_f32_e32 v142, v43
	v_exp_f32_e32 v139, v44
	v_exp_f32_e32 v141, v45
	v_exp_f32_e32 v136, v46
	v_exp_f32_e32 v138, v34
	v_exp_f32_e32 v135, v35
	v_exp_f32_e32 v137, v36
	v_and_b32_e32 v20, 15, v50
	v_readlane_b32 s2, v254, 30
	v_mov_b64_e32 v[16:17], s[26:27]
	s_waitcnt vmcnt(4)
	v_lshl_or_b32 v18, v20, 4, v18
	v_readlane_b32 s3, v254, 31
	v_mov_b64_e32 v[4:5], s[14:15]
	v_mov_b64_e32 v[6:7], s[16:17]
	v_mov_b64_e32 v[8:9], s[18:19]
	v_mov_b64_e32 v[10:11], s[20:21]
	v_mov_b64_e32 v[12:13], s[22:23]
	v_mov_b64_e32 v[14:15], s[24:25]
	v_pk_fma_f32 v[120:121], v[32:33], s[0:1], v[70:71] op_sel_hi:[1,0,0]
	v_pk_fma_f32 v[122:123], v[30:31], s[0:1], v[70:71] op_sel_hi:[1,0,0]
	v_pk_fma_f32 v[128:129], v[28:29], s[0:1], v[70:71] op_sel_hi:[1,0,0]
	v_pk_fma_f32 v[114:115], v[26:27], s[0:1], v[70:71] op_sel_hi:[1,0,0]
	v_pk_fma_f32 v[116:117], v[24:25], s[0:1], v[70:71] op_sel_hi:[1,0,0]
	v_pk_fma_f32 v[118:119], v[22:23], s[0:1], v[70:71] op_sel_hi:[1,0,0]
	v_lshl_add_u64 v[146:147], s[2:3], 0, v[18:19]
	v_mov_b64_e32 v[32:33], v[16:17]
	s_waitcnt vmcnt(7)
	ds_write_b128 v209, v[220:223] offset:16384
	s_waitcnt vmcnt(6)
	ds_write_b128 v210, v[224:227] offset:16384
	s_waitcnt vmcnt(5)
	ds_write_b128 v177, v[228:231] offset:49152
	s_waitcnt vmcnt(4)
	ds_write_b128 v208, v[232:235] offset:49152
	v_cmp_gt_u32_e64 s[0:1], 32, v72
	v_mov_b64_e32 v[30:31], v[14:15]
	v_mov_b64_e32 v[28:29], v[12:13]
	v_mov_b64_e32 v[26:27], v[10:11]
	v_mov_b64_e32 v[24:25], v[8:9]
	v_mov_b64_e32 v[22:23], v[6:7]
	v_mov_b64_e32 v[20:21], v[4:5]
	v_mov_b64_e32 v[18:19], v[2:3]
	v_mov_b32_e32 v34, 0
	v_mov_b32_e32 v35, v150
	v_mov_b32_e32 v36, v150
	v_mov_b32_e32 v37, v150
	v_mov_b32_e32 v38, v150
	v_mov_b32_e32 v39, v150
	v_mov_b32_e32 v40, v150
	v_mov_b32_e32 v41, v150
	v_mov_b32_e32 v42, v150
	v_mov_b32_e32 v43, v150
	v_mov_b32_e32 v44, v150
	v_mov_b32_e32 v45, v150
	v_mov_b32_e32 v46, v150
	v_mov_b32_e32 v47, v150
	v_mov_b32_e32 v48, v150
	v_mov_b32_e32 v49, v150
	v_mov_b32_e32 v50, 0
	v_mov_b32_e32 v52, v150
	v_mov_b32_e32 v53, v150
	v_mov_b32_e32 v54, v150
	v_mov_b32_e32 v55, v150
	v_mov_b32_e32 v56, v150
	v_mov_b32_e32 v57, v150
	v_mov_b32_e32 v58, v150
	v_mov_b32_e32 v59, v150
	v_mov_b32_e32 v60, v150
	v_mov_b32_e32 v61, v150
	v_mov_b32_e32 v62, v150
	v_mov_b32_e32 v63, v150
	v_mov_b32_e32 v64, v150
	v_mov_b32_e32 v65, v150
	s_waitcnt lgkmcnt(0)
	s_barrier
